# EpiQK epilogues by hand: layer-1 q|k tiles (rstd, head RMSNorm batched over the 8 row groups, gain loaded once, rope fragments prefetched 3 groups ahead into freed accumulators) and layer-0 head-norm
# speedup vs baseline: 1.0147x; 1.0040x over previous
.LBB0_201:
	s_and_b64 vcc, exec, s[0:1]
	s_cbranch_vccz .LBB0_203
	s_lshl_b32 s0, s7, 2
	s_add_i32 s0, s68, s0
	v_lshl_add_u32 v183, v155, 2, s0
	ds_read2_b32 v[244:245], v183 offset1:16
	ds_read2_b32 v[246:247], v183 offset0:32 offset1:48
	ds_read2_b32 v[248:249], v183 offset0:128 offset1:144
	ds_read2_b32 v[250:251], v183 offset0:160 offset1:176
	s_lshl_b32 s9, s72, 9
	s_cmp_lt_i32 s72, 4
	s_cselect_b32 s1, s74, s96
	s_cselect_b32 s0, s83, s86
	s_cselect_b32 s8, 11, 9
	s_mov_b32 s24, 0x9200000
	s_cselect_b32 s24, 0x7200000, s24
	s_cselect_b32 s9, s9, 0
	s_mov_b32 s42, 0x3e38aa3b
	s_cselect_b32 s42, s42, 1.0
	v_readlane_b32 s2, v255, 42
	s_lshl_b32 s2, s2, 1
	s_add_u32 s9, s9, s2
	s_add_u32 s24, s24, s9
	v_readlane_b32 s2, v254, 37
	v_readlane_b32 s3, v254, 38
	s_add_u32 s44, s2, s24
	s_addc_u32 s45, s3, 0
	s_mov_b32 s9, s42
	s_add_u32 s42, s2, 0x1f00000
	s_addc_u32 s43, s3, 0
	s_lshl_b32 s24, 16, s8
	v_lshlrev_b32_e32 v177, 2, v154
	global_load_dwordx4 v[128:131], v177, s[0:1]
	global_load_dwordx4 v[132:135], v177, s[0:1] offset:16
	global_load_dwordx4 v[136:139], v177, s[0:1] offset:128
	global_load_dwordx4 v[140:143], v177, s[0:1] offset:144
	v_lshl_add_u32 v176, s76, 8, v178
	v_and_b32_e32 v174, 0x7ff, v176
	v_lshl_add_u32 v177, v174, 8, v177
	v_lshlrev_b32_e32 v176, s8, v176
	v_lshl_add_u32 v176, v154, 1, v176
	global_load_dwordx4 v[188:191], v177, s[42:43] offset:16
	global_load_dwordx4 v[196:199], v177, s[42:43] offset:144
	global_load_dwordx4 v[184:187], v177, s[42:43]
	global_load_dwordx4 v[192:195], v177, s[42:43] offset:128
	s_add_u32 s42, s42, 0x1000
	s_addc_u32 s43, s43, 0
	global_load_dwordx4 v[204:207], v177, s[42:43] offset:16
	global_load_dwordx4 v[212:215], v177, s[42:43] offset:144
	global_load_dwordx4 v[200:203], v177, s[42:43]
	global_load_dwordx4 v[208:211], v177, s[42:43] offset:128
	s_add_u32 s42, s42, 0x1000
	s_addc_u32 s43, s43, 0
	global_load_dwordx4 v[220:223], v177, s[42:43] offset:16
	global_load_dwordx4 v[168:171], v177, s[42:43] offset:144
	global_load_dwordx4 v[216:219], v177, s[42:43]
	global_load_dwordx4 v[164:167], v177, s[42:43] offset:128
	s_add_u32 s42, s42, 0x1000
	s_addc_u32 s43, s43, 0
	s_waitcnt lgkmcnt(0)
	v_cmp_lt_i32_e32 vcc, v230, v228
	v_pk_mul_f32 v[124:125], v[124:125], v[244:245] op_sel_hi:[1,0]
	v_pk_mul_f32 v[126:127], v[126:127], v[244:245] op_sel_hi:[1,0]
	v_pk_mul_f32 v[120:121], v[120:121], v[244:245] op_sel_hi:[1,0]
	v_pk_mul_f32 v[122:123], v[122:123], v[244:245] op_sel_hi:[1,0]
	v_pk_mul_f32 v[92:93], v[92:93], v[244:245] op_sel_hi:[1,0]
	v_pk_mul_f32 v[94:95], v[94:95], v[244:245] op_sel_hi:[1,0]
	v_pk_mul_f32 v[88:89], v[88:89], v[244:245] op_sel_hi:[1,0]
	v_pk_mul_f32 v[90:91], v[90:91], v[244:245] op_sel_hi:[1,0]
	v_pk_mul_f32 v[172:173], v[124:125], v[124:125]
	v_pk_fma_f32 v[172:173], v[126:127], v[126:127], v[172:173]
	v_pk_fma_f32 v[172:173], v[120:121], v[120:121], v[172:173]
	v_pk_fma_f32 v[172:173], v[122:123], v[122:123], v[172:173]
	v_pk_fma_f32 v[172:173], v[92:93], v[92:93], v[172:173]
	v_pk_fma_f32 v[172:173], v[94:95], v[94:95], v[172:173]
	v_pk_fma_f32 v[172:173], v[88:89], v[88:89], v[172:173]
	v_pk_fma_f32 v[172:173], v[90:91], v[90:91], v[172:173]
	v_cndmask_b32_e32 v183, v226, v230, vcc
	v_cmp_lt_i32_e32 vcc, v229, v228
	v_lshlrev_b32_e32 v183, 2, v183
	v_add_f32_e32 v232, v172, v173
	v_pk_mul_f32 v[116:117], v[116:117], v[244:245] op_sel:[0,1] op_sel_hi:[1,1]
	v_pk_mul_f32 v[118:119], v[118:119], v[244:245] op_sel:[0,1] op_sel_hi:[1,1]
	v_pk_mul_f32 v[112:113], v[112:113], v[244:245] op_sel:[0,1] op_sel_hi:[1,1]
	v_pk_mul_f32 v[114:115], v[114:115], v[244:245] op_sel:[0,1] op_sel_hi:[1,1]
	v_pk_mul_f32 v[84:85], v[84:85], v[244:245] op_sel:[0,1] op_sel_hi:[1,1]
	v_pk_mul_f32 v[86:87], v[86:87], v[244:245] op_sel:[0,1] op_sel_hi:[1,1]
	v_pk_mul_f32 v[80:81], v[80:81], v[244:245] op_sel:[0,1] op_sel_hi:[1,1]
	v_pk_mul_f32 v[82:83], v[82:83], v[244:245] op_sel:[0,1] op_sel_hi:[1,1]
	v_pk_mul_f32 v[172:173], v[116:117], v[116:117]
	v_pk_fma_f32 v[172:173], v[118:119], v[118:119], v[172:173]
	v_pk_fma_f32 v[172:173], v[112:113], v[112:113], v[172:173]
	v_pk_fma_f32 v[172:173], v[114:115], v[114:115], v[172:173]
	v_pk_fma_f32 v[172:173], v[84:85], v[84:85], v[172:173]
	v_pk_fma_f32 v[172:173], v[86:87], v[86:87], v[172:173]
	v_pk_fma_f32 v[172:173], v[80:81], v[80:81], v[172:173]
	v_pk_fma_f32 v[172:173], v[82:83], v[82:83], v[172:173]
	v_cndmask_b32_e32 v174, v226, v229, vcc
	v_lshlrev_b32_e32 v174, 2, v174
	v_add_f32_e32 v233, v172, v173
	v_pk_mul_f32 v[108:109], v[108:109], v[246:247] op_sel_hi:[1,0]
	v_pk_mul_f32 v[110:111], v[110:111], v[246:247] op_sel_hi:[1,0]
	v_pk_mul_f32 v[104:105], v[104:105], v[246:247] op_sel_hi:[1,0]
	v_pk_mul_f32 v[106:107], v[106:107], v[246:247] op_sel_hi:[1,0]
	v_pk_mul_f32 v[76:77], v[76:77], v[246:247] op_sel_hi:[1,0]
	v_pk_mul_f32 v[78:79], v[78:79], v[246:247] op_sel_hi:[1,0]
	v_pk_mul_f32 v[72:73], v[72:73], v[246:247] op_sel_hi:[1,0]
	v_pk_mul_f32 v[74:75], v[74:75], v[246:247] op_sel_hi:[1,0]
	v_pk_mul_f32 v[172:173], v[108:109], v[108:109]
	v_pk_fma_f32 v[172:173], v[110:111], v[110:111], v[172:173]
	v_pk_fma_f32 v[172:173], v[104:105], v[104:105], v[172:173]
	v_pk_fma_f32 v[172:173], v[106:107], v[106:107], v[172:173]
	v_pk_fma_f32 v[172:173], v[76:77], v[76:77], v[172:173]
	v_pk_fma_f32 v[172:173], v[78:79], v[78:79], v[172:173]
	v_pk_fma_f32 v[172:173], v[72:73], v[72:73], v[172:173]
	v_pk_fma_f32 v[172:173], v[74:75], v[74:75], v[172:173]
	v_add_f32_e32 v234, v172, v173
	v_pk_mul_f32 v[100:101], v[100:101], v[246:247] op_sel:[0,1] op_sel_hi:[1,1]
	v_pk_mul_f32 v[102:103], v[102:103], v[246:247] op_sel:[0,1] op_sel_hi:[1,1]
	v_pk_mul_f32 v[96:97], v[96:97], v[246:247] op_sel:[0,1] op_sel_hi:[1,1]
	v_pk_mul_f32 v[98:99], v[98:99], v[246:247] op_sel:[0,1] op_sel_hi:[1,1]
	v_pk_mul_f32 v[68:69], v[68:69], v[246:247] op_sel:[0,1] op_sel_hi:[1,1]
	v_pk_mul_f32 v[70:71], v[70:71], v[246:247] op_sel:[0,1] op_sel_hi:[1,1]
	v_pk_mul_f32 v[64:65], v[64:65], v[246:247] op_sel:[0,1] op_sel_hi:[1,1]
	v_pk_mul_f32 v[66:67], v[66:67], v[246:247] op_sel:[0,1] op_sel_hi:[1,1]
	v_pk_mul_f32 v[172:173], v[100:101], v[100:101]
	v_pk_fma_f32 v[172:173], v[102:103], v[102:103], v[172:173]
	v_pk_fma_f32 v[172:173], v[96:97], v[96:97], v[172:173]
	v_pk_fma_f32 v[172:173], v[98:99], v[98:99], v[172:173]
	v_pk_fma_f32 v[172:173], v[68:69], v[68:69], v[172:173]
	v_pk_fma_f32 v[172:173], v[70:71], v[70:71], v[172:173]
	v_pk_fma_f32 v[172:173], v[64:65], v[64:65], v[172:173]
	v_pk_fma_f32 v[172:173], v[66:67], v[66:67], v[172:173]
	v_add_f32_e32 v235, v172, v173
	v_pk_mul_f32 v[60:61], v[60:61], v[248:249] op_sel_hi:[1,0]
	v_pk_mul_f32 v[62:63], v[62:63], v[248:249] op_sel_hi:[1,0]
	v_pk_mul_f32 v[56:57], v[56:57], v[248:249] op_sel_hi:[1,0]
	v_pk_mul_f32 v[58:59], v[58:59], v[248:249] op_sel_hi:[1,0]
	v_pk_mul_f32 v[28:29], v[28:29], v[248:249] op_sel_hi:[1,0]
	v_pk_mul_f32 v[30:31], v[30:31], v[248:249] op_sel_hi:[1,0]
	v_pk_mul_f32 v[24:25], v[24:25], v[248:249] op_sel_hi:[1,0]
	v_pk_mul_f32 v[26:27], v[26:27], v[248:249] op_sel_hi:[1,0]
	v_pk_mul_f32 v[172:173], v[60:61], v[60:61]
	v_pk_fma_f32 v[172:173], v[62:63], v[62:63], v[172:173]
	v_pk_fma_f32 v[172:173], v[56:57], v[56:57], v[172:173]
	v_pk_fma_f32 v[172:173], v[58:59], v[58:59], v[172:173]
	v_pk_fma_f32 v[172:173], v[28:29], v[28:29], v[172:173]
	v_pk_fma_f32 v[172:173], v[30:31], v[30:31], v[172:173]
	v_pk_fma_f32 v[172:173], v[24:25], v[24:25], v[172:173]
	v_pk_fma_f32 v[172:173], v[26:27], v[26:27], v[172:173]
	v_add_f32_e32 v236, v172, v173
	v_pk_mul_f32 v[52:53], v[52:53], v[248:249] op_sel:[0,1] op_sel_hi:[1,1]
	v_pk_mul_f32 v[54:55], v[54:55], v[248:249] op_sel:[0,1] op_sel_hi:[1,1]
	v_pk_mul_f32 v[48:49], v[48:49], v[248:249] op_sel:[0,1] op_sel_hi:[1,1]
	v_pk_mul_f32 v[50:51], v[50:51], v[248:249] op_sel:[0,1] op_sel_hi:[1,1]
	v_pk_mul_f32 v[20:21], v[20:21], v[248:249] op_sel:[0,1] op_sel_hi:[1,1]
	v_pk_mul_f32 v[22:23], v[22:23], v[248:249] op_sel:[0,1] op_sel_hi:[1,1]
	v_pk_mul_f32 v[16:17], v[16:17], v[248:249] op_sel:[0,1] op_sel_hi:[1,1]
	v_pk_mul_f32 v[18:19], v[18:19], v[248:249] op_sel:[0,1] op_sel_hi:[1,1]
	v_pk_mul_f32 v[172:173], v[52:53], v[52:53]
	v_pk_fma_f32 v[172:173], v[54:55], v[54:55], v[172:173]
	v_pk_fma_f32 v[172:173], v[48:49], v[48:49], v[172:173]
	v_pk_fma_f32 v[172:173], v[50:51], v[50:51], v[172:173]
	v_pk_fma_f32 v[172:173], v[20:21], v[20:21], v[172:173]
	v_pk_fma_f32 v[172:173], v[22:23], v[22:23], v[172:173]
	v_pk_fma_f32 v[172:173], v[16:17], v[16:17], v[172:173]
	v_pk_fma_f32 v[172:173], v[18:19], v[18:19], v[172:173]
	v_add_f32_e32 v237, v172, v173
	v_pk_mul_f32 v[44:45], v[44:45], v[250:251] op_sel_hi:[1,0]
	v_pk_mul_f32 v[46:47], v[46:47], v[250:251] op_sel_hi:[1,0]
	v_pk_mul_f32 v[40:41], v[40:41], v[250:251] op_sel_hi:[1,0]
	v_pk_mul_f32 v[42:43], v[42:43], v[250:251] op_sel_hi:[1,0]
	v_pk_mul_f32 v[12:13], v[12:13], v[250:251] op_sel_hi:[1,0]
	v_pk_mul_f32 v[14:15], v[14:15], v[250:251] op_sel_hi:[1,0]
	v_pk_mul_f32 v[8:9], v[8:9], v[250:251] op_sel_hi:[1,0]
	v_pk_mul_f32 v[10:11], v[10:11], v[250:251] op_sel_hi:[1,0]
	v_pk_mul_f32 v[172:173], v[44:45], v[44:45]
	v_pk_fma_f32 v[172:173], v[46:47], v[46:47], v[172:173]
	v_pk_fma_f32 v[172:173], v[40:41], v[40:41], v[172:173]
	v_pk_fma_f32 v[172:173], v[42:43], v[42:43], v[172:173]
	v_pk_fma_f32 v[172:173], v[12:13], v[12:13], v[172:173]
	v_pk_fma_f32 v[172:173], v[14:15], v[14:15], v[172:173]
	v_pk_fma_f32 v[172:173], v[8:9], v[8:9], v[172:173]
	v_pk_fma_f32 v[172:173], v[10:11], v[10:11], v[172:173]
	v_add_f32_e32 v240, v172, v173
	v_pk_mul_f32 v[36:37], v[36:37], v[250:251] op_sel:[0,1] op_sel_hi:[1,1]
	v_pk_mul_f32 v[38:39], v[38:39], v[250:251] op_sel:[0,1] op_sel_hi:[1,1]
	v_pk_mul_f32 v[32:33], v[32:33], v[250:251] op_sel:[0,1] op_sel_hi:[1,1]
	v_pk_mul_f32 v[34:35], v[34:35], v[250:251] op_sel:[0,1] op_sel_hi:[1,1]
	v_pk_mul_f32 v[4:5], v[4:5], v[250:251] op_sel:[0,1] op_sel_hi:[1,1]
	v_pk_mul_f32 v[6:7], v[6:7], v[250:251] op_sel:[0,1] op_sel_hi:[1,1]
	v_pk_mul_f32 v[0:1], v[0:1], v[250:251] op_sel:[0,1] op_sel_hi:[1,1]
	v_pk_mul_f32 v[2:3], v[2:3], v[250:251] op_sel:[0,1] op_sel_hi:[1,1]
	v_pk_mul_f32 v[172:173], v[36:37], v[36:37]
	v_pk_fma_f32 v[172:173], v[38:39], v[38:39], v[172:173]
	v_pk_fma_f32 v[172:173], v[32:33], v[32:33], v[172:173]
	v_pk_fma_f32 v[172:173], v[34:35], v[34:35], v[172:173]
	v_pk_fma_f32 v[172:173], v[4:5], v[4:5], v[172:173]
	v_pk_fma_f32 v[172:173], v[6:7], v[6:7], v[172:173]
	v_pk_fma_f32 v[172:173], v[0:1], v[0:1], v[172:173]
	v_pk_fma_f32 v[172:173], v[2:3], v[2:3], v[172:173]
	v_add_f32_e32 v241, v172, v173
	ds_bpermute_b32 v244, v183, v232
	ds_bpermute_b32 v245, v183, v233
	ds_bpermute_b32 v246, v183, v234
	ds_bpermute_b32 v247, v183, v235
	ds_bpermute_b32 v248, v183, v236
	ds_bpermute_b32 v249, v183, v237
	ds_bpermute_b32 v250, v183, v240
	ds_bpermute_b32 v251, v183, v241
	s_waitcnt lgkmcnt(6)
	v_pk_add_f32 v[232:233], v[232:233], v[244:245]
	s_waitcnt lgkmcnt(4)
	v_pk_add_f32 v[234:235], v[234:235], v[246:247]
	s_waitcnt lgkmcnt(2)
	v_pk_add_f32 v[236:237], v[236:237], v[248:249]
	s_waitcnt lgkmcnt(0)
	v_pk_add_f32 v[240:241], v[240:241], v[250:251]
	ds_bpermute_b32 v244, v174, v232
	ds_bpermute_b32 v245, v174, v233
	ds_bpermute_b32 v246, v174, v234
	ds_bpermute_b32 v247, v174, v235
	ds_bpermute_b32 v248, v174, v236
	ds_bpermute_b32 v249, v174, v237
	ds_bpermute_b32 v250, v174, v240
	ds_bpermute_b32 v251, v174, v241
	s_waitcnt lgkmcnt(6)
	v_pk_add_f32 v[232:233], v[232:233], v[244:245]
	s_waitcnt lgkmcnt(4)
	v_pk_add_f32 v[234:235], v[234:235], v[246:247]
	s_waitcnt lgkmcnt(2)
	v_pk_add_f32 v[236:237], v[236:237], v[248:249]
	s_waitcnt lgkmcnt(0)
	v_pk_add_f32 v[240:241], v[240:241], v[250:251]
	v_mul_f32_e32 v232, 0x3c800000, v232
	v_mul_f32_e32 v233, 0x3c800000, v233
	v_mul_f32_e32 v234, 0x3c800000, v234
	v_mul_f32_e32 v235, 0x3c800000, v235
	v_mul_f32_e32 v236, 0x3c800000, v236
	v_mul_f32_e32 v237, 0x3c800000, v237
	v_mul_f32_e32 v240, 0x3c800000, v240
	v_mul_f32_e32 v241, 0x3c800000, v241
	v_add_f32_e32 v232, 0x358637bd, v232
	v_add_f32_e32 v233, 0x358637bd, v233
	v_add_f32_e32 v234, 0x358637bd, v234
	v_add_f32_e32 v235, 0x358637bd, v235
	v_add_f32_e32 v236, 0x358637bd, v236
	v_add_f32_e32 v237, 0x358637bd, v237
	v_add_f32_e32 v240, 0x358637bd, v240
	v_add_f32_e32 v241, 0x358637bd, v241
	v_rsq_f32_e32 v232, v232
	v_rsq_f32_e32 v233, v233
	v_rsq_f32_e32 v234, v234
	v_rsq_f32_e32 v235, v235
	v_rsq_f32_e32 v236, v236
	v_rsq_f32_e32 v237, v237
	v_rsq_f32_e32 v240, v240
	v_rsq_f32_e32 v241, v241
	v_mul_f32_e32 v232, s9, v232
	v_mul_f32_e32 v233, s9, v233
	v_mul_f32_e32 v234, s9, v234
	v_mul_f32_e32 v235, s9, v235
	v_mul_f32_e32 v236, s9, v236
	v_mul_f32_e32 v237, s9, v237
	v_mul_f32_e32 v240, s9, v240
	v_mul_f32_e32 v241, s9, v241
	s_waitcnt vmcnt(12)
	v_pk_mul_f32 v[244:245], v[128:129], v[232:233] op_sel_hi:[1,0]
	v_pk_mul_f32 v[246:247], v[130:131], v[232:233] op_sel_hi:[1,0]
	v_pk_mul_f32 v[124:125], v[124:125], v[244:245]
	v_pk_mul_f32 v[126:127], v[126:127], v[246:247]
	v_pk_mul_f32 v[248:249], v[132:133], v[232:233] op_sel_hi:[1,0]
	v_pk_mul_f32 v[250:251], v[134:135], v[232:233] op_sel_hi:[1,0]
	s_waitcnt vmcnt(8)
	v_pk_mul_f32 v[172:173], v[184:185], v[124:125] op_sel:[1,1] op_sel_hi:[0,1]
	v_pk_mul_f32 v[174:175], v[186:187], v[126:127] op_sel:[1,1] op_sel_hi:[0,1]
	s_nop 0
	v_pk_fma_f32 v[124:125], v[184:185], v[124:125], v[172:173] op_sel_hi:[1,0,1] neg_lo:[0,0,1]
	v_pk_fma_f32 v[126:127], v[186:187], v[126:127], v[174:175] op_sel_hi:[1,0,1] neg_lo:[0,0,1]
	v_pk_mul_f32 v[120:121], v[120:121], v[248:249]
	v_pk_mul_f32 v[122:123], v[122:123], v[250:251]
	v_pk_mul_f32 v[244:245], v[136:137], v[232:233] op_sel_hi:[1,0]
	v_pk_mul_f32 v[246:247], v[138:139], v[232:233] op_sel_hi:[1,0]
	v_pk_mul_f32 v[172:173], v[188:189], v[120:121] op_sel:[1,1] op_sel_hi:[0,1]
	v_pk_mul_f32 v[174:175], v[190:191], v[122:123] op_sel:[1,1] op_sel_hi:[0,1]
	v_cvt_pk_bf16_f32 v124, v124, v125
	v_cvt_pk_bf16_f32 v125, v126, v127
	v_pk_fma_f32 v[120:121], v[188:189], v[120:121], v[172:173] op_sel_hi:[1,0,1] neg_lo:[0,0,1]
	v_pk_fma_f32 v[122:123], v[190:191], v[122:123], v[174:175] op_sel_hi:[1,0,1] neg_lo:[0,0,1]
	v_pk_mul_f32 v[92:93], v[92:93], v[244:245]
	v_pk_mul_f32 v[94:95], v[94:95], v[246:247]
	v_pk_mul_f32 v[248:249], v[140:141], v[232:233] op_sel_hi:[1,0]
	v_pk_mul_f32 v[250:251], v[142:143], v[232:233] op_sel_hi:[1,0]
	v_pk_mul_f32 v[172:173], v[192:193], v[92:93] op_sel:[1,1] op_sel_hi:[0,1]
	v_pk_mul_f32 v[174:175], v[194:195], v[94:95] op_sel:[1,1] op_sel_hi:[0,1]
	v_cvt_pk_bf16_f32 v126, v120, v121
	v_cvt_pk_bf16_f32 v127, v122, v123
	v_pk_fma_f32 v[92:93], v[192:193], v[92:93], v[172:173] op_sel_hi:[1,0,1] neg_lo:[0,0,1]
	v_pk_fma_f32 v[94:95], v[194:195], v[94:95], v[174:175] op_sel_hi:[1,0,1] neg_lo:[0,0,1]
	v_pk_mul_f32 v[88:89], v[88:89], v[248:249]
	v_pk_mul_f32 v[90:91], v[90:91], v[250:251]
	v_pk_mul_f32 v[244:245], v[128:129], v[232:233] op_sel:[0,1] op_sel_hi:[1,1]
	v_pk_mul_f32 v[246:247], v[130:131], v[232:233] op_sel:[0,1] op_sel_hi:[1,1]
	v_pk_mul_f32 v[172:173], v[196:197], v[88:89] op_sel:[1,1] op_sel_hi:[0,1]
	v_pk_mul_f32 v[174:175], v[198:199], v[90:91] op_sel:[1,1] op_sel_hi:[0,1]
	v_cvt_pk_bf16_f32 v92, v92, v93
	v_cvt_pk_bf16_f32 v93, v94, v95
	v_pk_fma_f32 v[88:89], v[196:197], v[88:89], v[172:173] op_sel_hi:[1,0,1] neg_lo:[0,0,1]
	v_pk_fma_f32 v[90:91], v[198:199], v[90:91], v[174:175] op_sel_hi:[1,0,1] neg_lo:[0,0,1]
	v_pk_mul_f32 v[116:117], v[116:117], v[244:245]
	v_pk_mul_f32 v[118:119], v[118:119], v[246:247]
	v_pk_mul_f32 v[248:249], v[132:133], v[232:233] op_sel:[0,1] op_sel_hi:[1,1]
	v_pk_mul_f32 v[250:251], v[134:135], v[232:233] op_sel:[0,1] op_sel_hi:[1,1]
	s_waitcnt vmcnt(4)
	v_pk_mul_f32 v[172:173], v[200:201], v[116:117] op_sel:[1,1] op_sel_hi:[0,1]
	v_pk_mul_f32 v[174:175], v[202:203], v[118:119] op_sel:[1,1] op_sel_hi:[0,1]
	v_cvt_pk_bf16_f32 v94, v88, v89
	v_cvt_pk_bf16_f32 v95, v90, v91
	global_store_dwordx4 v176, v[124:127], s[44:45]
	global_store_dwordx4 v176, v[92:95], s[44:45] offset:64
	s_add_u32 s44, s44, s24
	s_addc_u32 s45, s45, 0
	global_load_dwordx4 v[120:123], v177, s[42:43] offset:16
	global_load_dwordx4 v[88:91], v177, s[42:43] offset:144
	global_load_dwordx4 v[124:127], v177, s[42:43]
	global_load_dwordx4 v[92:95], v177, s[42:43] offset:128
	s_add_u32 s42, s42, 0x5000
	s_addc_u32 s43, s43, 0
	v_pk_fma_f32 v[116:117], v[200:201], v[116:117], v[172:173] op_sel_hi:[1,0,1] neg_lo:[0,0,1]
	v_pk_fma_f32 v[118:119], v[202:203], v[118:119], v[174:175] op_sel_hi:[1,0,1] neg_lo:[0,0,1]
	v_pk_mul_f32 v[112:113], v[112:113], v[248:249]
	v_pk_mul_f32 v[114:115], v[114:115], v[250:251]
	v_pk_mul_f32 v[244:245], v[136:137], v[232:233] op_sel:[0,1] op_sel_hi:[1,1]
	v_pk_mul_f32 v[246:247], v[138:139], v[232:233] op_sel:[0,1] op_sel_hi:[1,1]
	v_pk_mul_f32 v[172:173], v[204:205], v[112:113] op_sel:[1,1] op_sel_hi:[0,1]
	v_pk_mul_f32 v[174:175], v[206:207], v[114:115] op_sel:[1,1] op_sel_hi:[0,1]
	v_cvt_pk_bf16_f32 v116, v116, v117
	v_cvt_pk_bf16_f32 v117, v118, v119
	v_pk_fma_f32 v[112:113], v[204:205], v[112:113], v[172:173] op_sel_hi:[1,0,1] neg_lo:[0,0,1]
	v_pk_fma_f32 v[114:115], v[206:207], v[114:115], v[174:175] op_sel_hi:[1,0,1] neg_lo:[0,0,1]
	v_pk_mul_f32 v[84:85], v[84:85], v[244:245]
	v_pk_mul_f32 v[86:87], v[86:87], v[246:247]
	v_pk_mul_f32 v[248:249], v[140:141], v[232:233] op_sel:[0,1] op_sel_hi:[1,1]
	v_pk_mul_f32 v[250:251], v[142:143], v[232:233] op_sel:[0,1] op_sel_hi:[1,1]
	v_pk_mul_f32 v[172:173], v[208:209], v[84:85] op_sel:[1,1] op_sel_hi:[0,1]
	v_pk_mul_f32 v[174:175], v[210:211], v[86:87] op_sel:[1,1] op_sel_hi:[0,1]
	v_cvt_pk_bf16_f32 v118, v112, v113
	v_cvt_pk_bf16_f32 v119, v114, v115
	v_pk_fma_f32 v[84:85], v[208:209], v[84:85], v[172:173] op_sel_hi:[1,0,1] neg_lo:[0,0,1]
	v_pk_fma_f32 v[86:87], v[210:211], v[86:87], v[174:175] op_sel_hi:[1,0,1] neg_lo:[0,0,1]
	v_pk_mul_f32 v[80:81], v[80:81], v[248:249]
	v_pk_mul_f32 v[82:83], v[82:83], v[250:251]
	v_pk_mul_f32 v[244:245], v[128:129], v[234:235] op_sel_hi:[1,0]
	v_pk_mul_f32 v[246:247], v[130:131], v[234:235] op_sel_hi:[1,0]
	v_pk_mul_f32 v[172:173], v[212:213], v[80:81] op_sel:[1,1] op_sel_hi:[0,1]
	v_pk_mul_f32 v[174:175], v[214:215], v[82:83] op_sel:[1,1] op_sel_hi:[0,1]
	v_cvt_pk_bf16_f32 v84, v84, v85
	v_cvt_pk_bf16_f32 v85, v86, v87
	v_pk_fma_f32 v[80:81], v[212:213], v[80:81], v[172:173] op_sel_hi:[1,0,1] neg_lo:[0,0,1]
	v_pk_fma_f32 v[82:83], v[214:215], v[82:83], v[174:175] op_sel_hi:[1,0,1] neg_lo:[0,0,1]
	v_pk_mul_f32 v[108:109], v[108:109], v[244:245]
	v_pk_mul_f32 v[110:111], v[110:111], v[246:247]
	v_pk_mul_f32 v[248:249], v[132:133], v[234:235] op_sel_hi:[1,0]
	v_pk_mul_f32 v[250:251], v[134:135], v[234:235] op_sel_hi:[1,0]
	s_waitcnt vmcnt(6)
	v_pk_mul_f32 v[172:173], v[216:217], v[108:109] op_sel:[1,1] op_sel_hi:[0,1]
	v_pk_mul_f32 v[174:175], v[218:219], v[110:111] op_sel:[1,1] op_sel_hi:[0,1]
	v_cvt_pk_bf16_f32 v86, v80, v81
	v_cvt_pk_bf16_f32 v87, v82, v83
	global_store_dwordx4 v176, v[116:119], s[44:45]
	global_store_dwordx4 v176, v[84:87], s[44:45] offset:64
	s_add_u32 s44, s44, s24
	s_addc_u32 s45, s45, 0
	global_load_dwordx4 v[112:115], v177, s[42:43] offset:16
	global_load_dwordx4 v[80:83], v177, s[42:43] offset:144
	global_load_dwordx4 v[116:119], v177, s[42:43]
	global_load_dwordx4 v[84:87], v177, s[42:43] offset:128
	s_add_u32 s42, s42, 0x1000
	s_addc_u32 s43, s43, 0
	v_pk_fma_f32 v[108:109], v[216:217], v[108:109], v[172:173] op_sel_hi:[1,0,1] neg_lo:[0,0,1]
	v_pk_fma_f32 v[110:111], v[218:219], v[110:111], v[174:175] op_sel_hi:[1,0,1] neg_lo:[0,0,1]
	v_pk_mul_f32 v[104:105], v[104:105], v[248:249]
	v_pk_mul_f32 v[106:107], v[106:107], v[250:251]
	v_pk_mul_f32 v[244:245], v[136:137], v[234:235] op_sel_hi:[1,0]
	v_pk_mul_f32 v[246:247], v[138:139], v[234:235] op_sel_hi:[1,0]
	v_pk_mul_f32 v[172:173], v[220:221], v[104:105] op_sel:[1,1] op_sel_hi:[0,1]
	v_pk_mul_f32 v[174:175], v[222:223], v[106:107] op_sel:[1,1] op_sel_hi:[0,1]
	v_cvt_pk_bf16_f32 v108, v108, v109
	v_cvt_pk_bf16_f32 v109, v110, v111
	v_pk_fma_f32 v[104:105], v[220:221], v[104:105], v[172:173] op_sel_hi:[1,0,1] neg_lo:[0,0,1]
	v_pk_fma_f32 v[106:107], v[222:223], v[106:107], v[174:175] op_sel_hi:[1,0,1] neg_lo:[0,0,1]
	v_pk_mul_f32 v[76:77], v[76:77], v[244:245]
	v_pk_mul_f32 v[78:79], v[78:79], v[246:247]
	v_pk_mul_f32 v[248:249], v[140:141], v[234:235] op_sel_hi:[1,0]
	v_pk_mul_f32 v[250:251], v[142:143], v[234:235] op_sel_hi:[1,0]
	v_pk_mul_f32 v[172:173], v[164:165], v[76:77] op_sel:[1,1] op_sel_hi:[0,1]
	v_pk_mul_f32 v[174:175], v[166:167], v[78:79] op_sel:[1,1] op_sel_hi:[0,1]
	v_cvt_pk_bf16_f32 v110, v104, v105
	v_cvt_pk_bf16_f32 v111, v106, v107
	v_pk_fma_f32 v[76:77], v[164:165], v[76:77], v[172:173] op_sel_hi:[1,0,1] neg_lo:[0,0,1]
	v_pk_fma_f32 v[78:79], v[166:167], v[78:79], v[174:175] op_sel_hi:[1,0,1] neg_lo:[0,0,1]
	v_pk_mul_f32 v[72:73], v[72:73], v[248:249]
	v_pk_mul_f32 v[74:75], v[74:75], v[250:251]
	v_pk_mul_f32 v[244:245], v[128:129], v[234:235] op_sel:[0,1] op_sel_hi:[1,1]
	v_pk_mul_f32 v[246:247], v[130:131], v[234:235] op_sel:[0,1] op_sel_hi:[1,1]
	v_pk_mul_f32 v[172:173], v[168:169], v[72:73] op_sel:[1,1] op_sel_hi:[0,1]
	v_pk_mul_f32 v[174:175], v[170:171], v[74:75] op_sel:[1,1] op_sel_hi:[0,1]
	v_cvt_pk_bf16_f32 v76, v76, v77
	v_cvt_pk_bf16_f32 v77, v78, v79
	v_pk_fma_f32 v[72:73], v[168:169], v[72:73], v[172:173] op_sel_hi:[1,0,1] neg_lo:[0,0,1]
	v_pk_fma_f32 v[74:75], v[170:171], v[74:75], v[174:175] op_sel_hi:[1,0,1] neg_lo:[0,0,1]
	v_pk_mul_f32 v[100:101], v[100:101], v[244:245]
	v_pk_mul_f32 v[102:103], v[102:103], v[246:247]
	v_pk_mul_f32 v[248:249], v[132:133], v[234:235] op_sel:[0,1] op_sel_hi:[1,1]
	v_pk_mul_f32 v[250:251], v[134:135], v[234:235] op_sel:[0,1] op_sel_hi:[1,1]
	s_waitcnt vmcnt(6)
	v_pk_mul_f32 v[172:173], v[124:125], v[100:101] op_sel:[1,1] op_sel_hi:[0,1]
	v_pk_mul_f32 v[174:175], v[126:127], v[102:103] op_sel:[1,1] op_sel_hi:[0,1]
	v_cvt_pk_bf16_f32 v78, v72, v73
	v_cvt_pk_bf16_f32 v79, v74, v75
	global_store_dwordx4 v176, v[108:111], s[44:45]
	global_store_dwordx4 v176, v[76:79], s[44:45] offset:64
	s_add_u32 s44, s44, s24
	s_addc_u32 s45, s45, 0
	global_load_dwordx4 v[104:107], v177, s[42:43] offset:16
	global_load_dwordx4 v[72:75], v177, s[42:43] offset:144
	global_load_dwordx4 v[108:111], v177, s[42:43]
	global_load_dwordx4 v[76:79], v177, s[42:43] offset:128
	s_add_u32 s42, s42, 0x1000
	s_addc_u32 s43, s43, 0
	v_pk_fma_f32 v[100:101], v[124:125], v[100:101], v[172:173] op_sel_hi:[1,0,1] neg_lo:[0,0,1]
	v_pk_fma_f32 v[102:103], v[126:127], v[102:103], v[174:175] op_sel_hi:[1,0,1] neg_lo:[0,0,1]
	v_pk_mul_f32 v[96:97], v[96:97], v[248:249]
	v_pk_mul_f32 v[98:99], v[98:99], v[250:251]
	v_pk_mul_f32 v[244:245], v[136:137], v[234:235] op_sel:[0,1] op_sel_hi:[1,1]
	v_pk_mul_f32 v[246:247], v[138:139], v[234:235] op_sel:[0,1] op_sel_hi:[1,1]
	v_pk_mul_f32 v[172:173], v[120:121], v[96:97] op_sel:[1,1] op_sel_hi:[0,1]
	v_pk_mul_f32 v[174:175], v[122:123], v[98:99] op_sel:[1,1] op_sel_hi:[0,1]
	v_cvt_pk_bf16_f32 v100, v100, v101
	v_cvt_pk_bf16_f32 v101, v102, v103
	v_pk_fma_f32 v[96:97], v[120:121], v[96:97], v[172:173] op_sel_hi:[1,0,1] neg_lo:[0,0,1]
	v_pk_fma_f32 v[98:99], v[122:123], v[98:99], v[174:175] op_sel_hi:[1,0,1] neg_lo:[0,0,1]
	v_pk_mul_f32 v[68:69], v[68:69], v[244:245]
	v_pk_mul_f32 v[70:71], v[70:71], v[246:247]
	v_pk_mul_f32 v[248:249], v[140:141], v[234:235] op_sel:[0,1] op_sel_hi:[1,1]
	v_pk_mul_f32 v[250:251], v[142:143], v[234:235] op_sel:[0,1] op_sel_hi:[1,1]
	v_pk_mul_f32 v[172:173], v[92:93], v[68:69] op_sel:[1,1] op_sel_hi:[0,1]
	v_pk_mul_f32 v[174:175], v[94:95], v[70:71] op_sel:[1,1] op_sel_hi:[0,1]
	v_cvt_pk_bf16_f32 v102, v96, v97
	v_cvt_pk_bf16_f32 v103, v98, v99
	v_pk_fma_f32 v[68:69], v[92:93], v[68:69], v[172:173] op_sel_hi:[1,0,1] neg_lo:[0,0,1]
	v_pk_fma_f32 v[70:71], v[94:95], v[70:71], v[174:175] op_sel_hi:[1,0,1] neg_lo:[0,0,1]
	v_pk_mul_f32 v[64:65], v[64:65], v[248:249]
	v_pk_mul_f32 v[66:67], v[66:67], v[250:251]
	v_pk_mul_f32 v[244:245], v[128:129], v[236:237] op_sel_hi:[1,0]
	v_pk_mul_f32 v[246:247], v[130:131], v[236:237] op_sel_hi:[1,0]
	v_pk_mul_f32 v[172:173], v[88:89], v[64:65] op_sel:[1,1] op_sel_hi:[0,1]
	v_pk_mul_f32 v[174:175], v[90:91], v[66:67] op_sel:[1,1] op_sel_hi:[0,1]
	v_cvt_pk_bf16_f32 v68, v68, v69
	v_cvt_pk_bf16_f32 v69, v70, v71
	v_pk_fma_f32 v[64:65], v[88:89], v[64:65], v[172:173] op_sel_hi:[1,0,1] neg_lo:[0,0,1]
	v_pk_fma_f32 v[66:67], v[90:91], v[66:67], v[174:175] op_sel_hi:[1,0,1] neg_lo:[0,0,1]
	v_pk_mul_f32 v[60:61], v[60:61], v[244:245]
	v_pk_mul_f32 v[62:63], v[62:63], v[246:247]
	v_pk_mul_f32 v[248:249], v[132:133], v[236:237] op_sel_hi:[1,0]
	v_pk_mul_f32 v[250:251], v[134:135], v[236:237] op_sel_hi:[1,0]
	s_waitcnt vmcnt(6)
	v_pk_mul_f32 v[172:173], v[116:117], v[60:61] op_sel:[1,1] op_sel_hi:[0,1]
	v_pk_mul_f32 v[174:175], v[118:119], v[62:63] op_sel:[1,1] op_sel_hi:[0,1]
	v_cvt_pk_bf16_f32 v70, v64, v65
	v_cvt_pk_bf16_f32 v71, v66, v67
	global_store_dwordx4 v176, v[100:103], s[44:45]
	global_store_dwordx4 v176, v[68:71], s[44:45] offset:64
	s_lshl_b32 s2, 0x50, s8
	s_add_u32 s44, s44, s2
	s_addc_u32 s45, s45, 0
	global_load_dwordx4 v[96:99], v177, s[42:43] offset:16
	global_load_dwordx4 v[64:67], v177, s[42:43] offset:144
	global_load_dwordx4 v[100:103], v177, s[42:43]
	global_load_dwordx4 v[68:71], v177, s[42:43] offset:128
	s_add_u32 s42, s42, 0x1000
	s_addc_u32 s43, s43, 0
	v_pk_fma_f32 v[60:61], v[116:117], v[60:61], v[172:173] op_sel_hi:[1,0,1] neg_lo:[0,0,1]
	v_pk_fma_f32 v[62:63], v[118:119], v[62:63], v[174:175] op_sel_hi:[1,0,1] neg_lo:[0,0,1]
	v_pk_mul_f32 v[56:57], v[56:57], v[248:249]
	v_pk_mul_f32 v[58:59], v[58:59], v[250:251]
	v_pk_mul_f32 v[244:245], v[136:137], v[236:237] op_sel_hi:[1,0]
	v_pk_mul_f32 v[246:247], v[138:139], v[236:237] op_sel_hi:[1,0]
	v_pk_mul_f32 v[172:173], v[112:113], v[56:57] op_sel:[1,1] op_sel_hi:[0,1]
	v_pk_mul_f32 v[174:175], v[114:115], v[58:59] op_sel:[1,1] op_sel_hi:[0,1]
	v_cvt_pk_bf16_f32 v60, v60, v61
	v_cvt_pk_bf16_f32 v61, v62, v63
	v_pk_fma_f32 v[56:57], v[112:113], v[56:57], v[172:173] op_sel_hi:[1,0,1] neg_lo:[0,0,1]
	v_pk_fma_f32 v[58:59], v[114:115], v[58:59], v[174:175] op_sel_hi:[1,0,1] neg_lo:[0,0,1]
	v_pk_mul_f32 v[28:29], v[28:29], v[244:245]
	v_pk_mul_f32 v[30:31], v[30:31], v[246:247]
	v_pk_mul_f32 v[248:249], v[140:141], v[236:237] op_sel_hi:[1,0]
	v_pk_mul_f32 v[250:251], v[142:143], v[236:237] op_sel_hi:[1,0]
	v_pk_mul_f32 v[172:173], v[84:85], v[28:29] op_sel:[1,1] op_sel_hi:[0,1]
	v_pk_mul_f32 v[174:175], v[86:87], v[30:31] op_sel:[1,1] op_sel_hi:[0,1]
	v_cvt_pk_bf16_f32 v62, v56, v57
	v_cvt_pk_bf16_f32 v63, v58, v59
	v_pk_fma_f32 v[28:29], v[84:85], v[28:29], v[172:173] op_sel_hi:[1,0,1] neg_lo:[0,0,1]
	v_pk_fma_f32 v[30:31], v[86:87], v[30:31], v[174:175] op_sel_hi:[1,0,1] neg_lo:[0,0,1]
	v_pk_mul_f32 v[24:25], v[24:25], v[248:249]
	v_pk_mul_f32 v[26:27], v[26:27], v[250:251]
	v_pk_mul_f32 v[244:245], v[128:129], v[236:237] op_sel:[0,1] op_sel_hi:[1,1]
	v_pk_mul_f32 v[246:247], v[130:131], v[236:237] op_sel:[0,1] op_sel_hi:[1,1]
	v_pk_mul_f32 v[172:173], v[80:81], v[24:25] op_sel:[1,1] op_sel_hi:[0,1]
	v_pk_mul_f32 v[174:175], v[82:83], v[26:27] op_sel:[1,1] op_sel_hi:[0,1]
	v_cvt_pk_bf16_f32 v28, v28, v29
	v_cvt_pk_bf16_f32 v29, v30, v31
	v_pk_fma_f32 v[24:25], v[80:81], v[24:25], v[172:173] op_sel_hi:[1,0,1] neg_lo:[0,0,1]
	v_pk_fma_f32 v[26:27], v[82:83], v[26:27], v[174:175] op_sel_hi:[1,0,1] neg_lo:[0,0,1]
	v_pk_mul_f32 v[52:53], v[52:53], v[244:245]
	v_pk_mul_f32 v[54:55], v[54:55], v[246:247]
	v_pk_mul_f32 v[248:249], v[132:133], v[236:237] op_sel:[0,1] op_sel_hi:[1,1]
	v_pk_mul_f32 v[250:251], v[134:135], v[236:237] op_sel:[0,1] op_sel_hi:[1,1]
	s_waitcnt vmcnt(6)
	v_pk_mul_f32 v[172:173], v[108:109], v[52:53] op_sel:[1,1] op_sel_hi:[0,1]
	v_pk_mul_f32 v[174:175], v[110:111], v[54:55] op_sel:[1,1] op_sel_hi:[0,1]
	v_cvt_pk_bf16_f32 v30, v24, v25
	v_cvt_pk_bf16_f32 v31, v26, v27
	global_store_dwordx4 v176, v[60:63], s[44:45]
	global_store_dwordx4 v176, v[28:31], s[44:45] offset:64
	s_add_u32 s44, s44, s24
	s_addc_u32 s45, s45, 0
	global_load_dwordx4 v[56:59], v177, s[42:43] offset:16
	global_load_dwordx4 v[24:27], v177, s[42:43] offset:144
	global_load_dwordx4 v[60:63], v177, s[42:43]
	global_load_dwordx4 v[28:31], v177, s[42:43] offset:128
	v_pk_fma_f32 v[52:53], v[108:109], v[52:53], v[172:173] op_sel_hi:[1,0,1] neg_lo:[0,0,1]
	v_pk_fma_f32 v[54:55], v[110:111], v[54:55], v[174:175] op_sel_hi:[1,0,1] neg_lo:[0,0,1]
	v_pk_mul_f32 v[48:49], v[48:49], v[248:249]
	v_pk_mul_f32 v[50:51], v[50:51], v[250:251]
	v_pk_mul_f32 v[244:245], v[136:137], v[236:237] op_sel:[0,1] op_sel_hi:[1,1]
	v_pk_mul_f32 v[246:247], v[138:139], v[236:237] op_sel:[0,1] op_sel_hi:[1,1]
	v_pk_mul_f32 v[172:173], v[104:105], v[48:49] op_sel:[1,1] op_sel_hi:[0,1]
	v_pk_mul_f32 v[174:175], v[106:107], v[50:51] op_sel:[1,1] op_sel_hi:[0,1]
	v_cvt_pk_bf16_f32 v52, v52, v53
	v_cvt_pk_bf16_f32 v53, v54, v55
	v_pk_fma_f32 v[48:49], v[104:105], v[48:49], v[172:173] op_sel_hi:[1,0,1] neg_lo:[0,0,1]
	v_pk_fma_f32 v[50:51], v[106:107], v[50:51], v[174:175] op_sel_hi:[1,0,1] neg_lo:[0,0,1]
	v_pk_mul_f32 v[20:21], v[20:21], v[244:245]
	v_pk_mul_f32 v[22:23], v[22:23], v[246:247]
	v_pk_mul_f32 v[248:249], v[140:141], v[236:237] op_sel:[0,1] op_sel_hi:[1,1]
	v_pk_mul_f32 v[250:251], v[142:143], v[236:237] op_sel:[0,1] op_sel_hi:[1,1]
	v_pk_mul_f32 v[172:173], v[76:77], v[20:21] op_sel:[1,1] op_sel_hi:[0,1]
	v_pk_mul_f32 v[174:175], v[78:79], v[22:23] op_sel:[1,1] op_sel_hi:[0,1]
	v_cvt_pk_bf16_f32 v54, v48, v49
	v_cvt_pk_bf16_f32 v55, v50, v51
	v_pk_fma_f32 v[20:21], v[76:77], v[20:21], v[172:173] op_sel_hi:[1,0,1] neg_lo:[0,0,1]
	v_pk_fma_f32 v[22:23], v[78:79], v[22:23], v[174:175] op_sel_hi:[1,0,1] neg_lo:[0,0,1]
	v_pk_mul_f32 v[16:17], v[16:17], v[248:249]
	v_pk_mul_f32 v[18:19], v[18:19], v[250:251]
	v_pk_mul_f32 v[244:245], v[128:129], v[240:241] op_sel_hi:[1,0]
	v_pk_mul_f32 v[246:247], v[130:131], v[240:241] op_sel_hi:[1,0]
	v_pk_mul_f32 v[172:173], v[72:73], v[16:17] op_sel:[1,1] op_sel_hi:[0,1]
	v_pk_mul_f32 v[174:175], v[74:75], v[18:19] op_sel:[1,1] op_sel_hi:[0,1]
	v_cvt_pk_bf16_f32 v20, v20, v21
	v_cvt_pk_bf16_f32 v21, v22, v23
	v_pk_fma_f32 v[16:17], v[72:73], v[16:17], v[172:173] op_sel_hi:[1,0,1] neg_lo:[0,0,1]
	v_pk_fma_f32 v[18:19], v[74:75], v[18:19], v[174:175] op_sel_hi:[1,0,1] neg_lo:[0,0,1]
	v_pk_mul_f32 v[44:45], v[44:45], v[244:245]
	v_pk_mul_f32 v[46:47], v[46:47], v[246:247]
	v_pk_mul_f32 v[248:249], v[132:133], v[240:241] op_sel_hi:[1,0]
	v_pk_mul_f32 v[250:251], v[134:135], v[240:241] op_sel_hi:[1,0]
	s_waitcnt vmcnt(6)
	v_pk_mul_f32 v[172:173], v[100:101], v[44:45] op_sel:[1,1] op_sel_hi:[0,1]
	v_pk_mul_f32 v[174:175], v[102:103], v[46:47] op_sel:[1,1] op_sel_hi:[0,1]
	v_cvt_pk_bf16_f32 v22, v16, v17
	v_cvt_pk_bf16_f32 v23, v18, v19
	global_store_dwordx4 v176, v[52:55], s[44:45]
	global_store_dwordx4 v176, v[20:23], s[44:45] offset:64
	s_add_u32 s44, s44, s24
	s_addc_u32 s45, s45, 0
	v_pk_fma_f32 v[44:45], v[100:101], v[44:45], v[172:173] op_sel_hi:[1,0,1] neg_lo:[0,0,1]
	v_pk_fma_f32 v[46:47], v[102:103], v[46:47], v[174:175] op_sel_hi:[1,0,1] neg_lo:[0,0,1]
	v_pk_mul_f32 v[40:41], v[40:41], v[248:249]
	v_pk_mul_f32 v[42:43], v[42:43], v[250:251]
	v_pk_mul_f32 v[244:245], v[136:137], v[240:241] op_sel_hi:[1,0]
	v_pk_mul_f32 v[246:247], v[138:139], v[240:241] op_sel_hi:[1,0]
	v_pk_mul_f32 v[172:173], v[96:97], v[40:41] op_sel:[1,1] op_sel_hi:[0,1]
	v_pk_mul_f32 v[174:175], v[98:99], v[42:43] op_sel:[1,1] op_sel_hi:[0,1]
	v_cvt_pk_bf16_f32 v44, v44, v45
	v_cvt_pk_bf16_f32 v45, v46, v47
	v_pk_fma_f32 v[40:41], v[96:97], v[40:41], v[172:173] op_sel_hi:[1,0,1] neg_lo:[0,0,1]
	v_pk_fma_f32 v[42:43], v[98:99], v[42:43], v[174:175] op_sel_hi:[1,0,1] neg_lo:[0,0,1]
	v_pk_mul_f32 v[12:13], v[12:13], v[244:245]
	v_pk_mul_f32 v[14:15], v[14:15], v[246:247]
	v_pk_mul_f32 v[248:249], v[140:141], v[240:241] op_sel_hi:[1,0]
	v_pk_mul_f32 v[250:251], v[142:143], v[240:241] op_sel_hi:[1,0]
	v_pk_mul_f32 v[172:173], v[68:69], v[12:13] op_sel:[1,1] op_sel_hi:[0,1]
	v_pk_mul_f32 v[174:175], v[70:71], v[14:15] op_sel:[1,1] op_sel_hi:[0,1]
	v_cvt_pk_bf16_f32 v46, v40, v41
	v_cvt_pk_bf16_f32 v47, v42, v43
	v_pk_fma_f32 v[12:13], v[68:69], v[12:13], v[172:173] op_sel_hi:[1,0,1] neg_lo:[0,0,1]
	v_pk_fma_f32 v[14:15], v[70:71], v[14:15], v[174:175] op_sel_hi:[1,0,1] neg_lo:[0,0,1]
	v_pk_mul_f32 v[8:9], v[8:9], v[248:249]
	v_pk_mul_f32 v[10:11], v[10:11], v[250:251]
	v_pk_mul_f32 v[244:245], v[128:129], v[240:241] op_sel:[0,1] op_sel_hi:[1,1]
	v_pk_mul_f32 v[246:247], v[130:131], v[240:241] op_sel:[0,1] op_sel_hi:[1,1]
	v_pk_mul_f32 v[172:173], v[64:65], v[8:9] op_sel:[1,1] op_sel_hi:[0,1]
	v_pk_mul_f32 v[174:175], v[66:67], v[10:11] op_sel:[1,1] op_sel_hi:[0,1]
	v_cvt_pk_bf16_f32 v12, v12, v13
	v_cvt_pk_bf16_f32 v13, v14, v15
	v_pk_fma_f32 v[8:9], v[64:65], v[8:9], v[172:173] op_sel_hi:[1,0,1] neg_lo:[0,0,1]
	v_pk_fma_f32 v[10:11], v[66:67], v[10:11], v[174:175] op_sel_hi:[1,0,1] neg_lo:[0,0,1]
	v_pk_mul_f32 v[36:37], v[36:37], v[244:245]
	v_pk_mul_f32 v[38:39], v[38:39], v[246:247]
	v_pk_mul_f32 v[248:249], v[132:133], v[240:241] op_sel:[0,1] op_sel_hi:[1,1]
	v_pk_mul_f32 v[250:251], v[134:135], v[240:241] op_sel:[0,1] op_sel_hi:[1,1]
	s_waitcnt vmcnt(2)
	v_pk_mul_f32 v[172:173], v[60:61], v[36:37] op_sel:[1,1] op_sel_hi:[0,1]
	v_pk_mul_f32 v[174:175], v[62:63], v[38:39] op_sel:[1,1] op_sel_hi:[0,1]
	v_cvt_pk_bf16_f32 v14, v8, v9
	v_cvt_pk_bf16_f32 v15, v10, v11
	global_store_dwordx4 v176, v[44:47], s[44:45]
	global_store_dwordx4 v176, v[12:15], s[44:45] offset:64
	s_add_u32 s44, s44, s24
	s_addc_u32 s45, s45, 0
	v_pk_fma_f32 v[36:37], v[60:61], v[36:37], v[172:173] op_sel_hi:[1,0,1] neg_lo:[0,0,1]
	v_pk_fma_f32 v[38:39], v[62:63], v[38:39], v[174:175] op_sel_hi:[1,0,1] neg_lo:[0,0,1]
	v_pk_mul_f32 v[32:33], v[32:33], v[248:249]
	v_pk_mul_f32 v[34:35], v[34:35], v[250:251]
	v_pk_mul_f32 v[244:245], v[136:137], v[240:241] op_sel:[0,1] op_sel_hi:[1,1]
	v_pk_mul_f32 v[246:247], v[138:139], v[240:241] op_sel:[0,1] op_sel_hi:[1,1]
	v_pk_mul_f32 v[172:173], v[56:57], v[32:33] op_sel:[1,1] op_sel_hi:[0,1]
	v_pk_mul_f32 v[174:175], v[58:59], v[34:35] op_sel:[1,1] op_sel_hi:[0,1]
	v_cvt_pk_bf16_f32 v36, v36, v37
	v_cvt_pk_bf16_f32 v37, v38, v39
	v_pk_fma_f32 v[32:33], v[56:57], v[32:33], v[172:173] op_sel_hi:[1,0,1] neg_lo:[0,0,1]
	v_pk_fma_f32 v[34:35], v[58:59], v[34:35], v[174:175] op_sel_hi:[1,0,1] neg_lo:[0,0,1]
	v_pk_mul_f32 v[4:5], v[4:5], v[244:245]
	v_pk_mul_f32 v[6:7], v[6:7], v[246:247]
	v_pk_mul_f32 v[248:249], v[140:141], v[240:241] op_sel:[0,1] op_sel_hi:[1,1]
	v_pk_mul_f32 v[250:251], v[142:143], v[240:241] op_sel:[0,1] op_sel_hi:[1,1]
	v_pk_mul_f32 v[172:173], v[28:29], v[4:5] op_sel:[1,1] op_sel_hi:[0,1]
	v_pk_mul_f32 v[174:175], v[30:31], v[6:7] op_sel:[1,1] op_sel_hi:[0,1]
	v_cvt_pk_bf16_f32 v38, v32, v33
	v_cvt_pk_bf16_f32 v39, v34, v35
	v_pk_fma_f32 v[4:5], v[28:29], v[4:5], v[172:173] op_sel_hi:[1,0,1] neg_lo:[0,0,1]
	v_pk_fma_f32 v[6:7], v[30:31], v[6:7], v[174:175] op_sel_hi:[1,0,1] neg_lo:[0,0,1]
	v_pk_mul_f32 v[0:1], v[0:1], v[248:249]
	v_pk_mul_f32 v[2:3], v[2:3], v[250:251]
	v_pk_mul_f32 v[172:173], v[24:25], v[0:1] op_sel:[1,1] op_sel_hi:[0,1]
	v_pk_mul_f32 v[174:175], v[26:27], v[2:3] op_sel:[1,1] op_sel_hi:[0,1]
	v_cvt_pk_bf16_f32 v4, v4, v5
	v_cvt_pk_bf16_f32 v5, v6, v7
	v_pk_fma_f32 v[0:1], v[24:25], v[0:1], v[172:173] op_sel_hi:[1,0,1] neg_lo:[0,0,1]
	v_pk_fma_f32 v[2:3], v[26:27], v[2:3], v[174:175] op_sel_hi:[1,0,1] neg_lo:[0,0,1]
	s_nop 0
	v_cvt_pk_bf16_f32 v6, v0, v1
	v_cvt_pk_bf16_f32 v7, v2, v3
	global_store_dwordx4 v176, v[36:39], s[44:45]
	global_store_dwordx4 v176, v[4:7], s[44:45] offset:64

.LBB0_204:
	s_andn2_b64 vcc, exec, s[0:1]
	s_cbranch_vccnz .LBB0_317
	s_cmp_lt_i32 s72, 4
	s_cbranch_scc1 .Lqk0_hn
	s_cmp_gt_i32 s72, 3
	s_cselect_b64 s[44:45], -1, 0
	s_cmp_gt_u32 s72, 7
	s_cselect_b64 s[60:61], -1, 0
	s_cmp_gt_u32 s72, 15
	s_mov_b32 s34, s78
	s_cselect_b64 s[78:79], -1, 0
	s_lshl_b32 s8, s72, 8
	s_cmp_lt_i32 s72, 2
	s_cselect_b64 s[42:43], -1, 0
	v_lshl_add_u32 v128, s76, 8, v178
	s_and_b64 s[46:47], s[42:43], exec
	s_mov_b32 s9, 0x4200000
	s_cselect_b32 s81, s9, 0x5200000
	v_ashrrev_i32_e32 v129, 31, v128
	s_mov_b64 s[46:47], -1
	s_and_b64 vcc, exec, s[44:45]
	s_cbranch_vccz .LBB0_217
	s_and_b64 vcc, exec, s[60:61]
	s_cbranch_vccz .LBB0_214
	s_and_b64 vcc, exec, s[78:79]
	s_cbranch_vccz .LBB0_211
	v_readlane_b32 s0, v255, 43
	v_readlane_b32 s1, v255, 44
	s_andn2_b64 vcc, exec, s[0:1]
	s_cbranch_vccnz .LBB0_210
	v_lshlrev_b64 v[130:131], 7, v[128:129]
	v_lshl_add_u64 v[130:131], v[156:157], 0, v[130:131]
	global_store_dwordx4 v[130:131], v[124:127], off
	global_store_dwordx4 v[130:131], v[120:123], off offset:16

.Ler_h7_n:
.Ler_done:
	s_branch .LBB0_611
.Lqk0_hn:
	s_and_b32 s2, s72, 1
	s_lshl_b32 s2, s2, 9
	s_lshl_b32 s3, s5, 7
	s_add_u32 s2, s2, s3
	s_cmp_lt_i32 s72, 2
	s_cselect_b32 s1, s74, s96
	s_cselect_b32 s0, s83, s86
	s_mov_b32 s24, 0x5200000
	s_cselect_b32 s24, 0x4200000, s24
	s_mov_b32 s9, 0x3e38aa3b
	s_cselect_b32 s9, s9, 1.0
	s_add_u32 s24, s24, s2
	v_readlane_b32 s2, v254, 37
	v_readlane_b32 s3, v254, 38
	s_add_u32 s44, s2, s24
	s_addc_u32 s45, s3, 0
	v_lshlrev_b32_e32 v177, 2, v154
	global_load_dwordx4 v[128:131], v177, s[0:1]
	global_load_dwordx4 v[132:135], v177, s[0:1] offset:16
	global_load_dwordx4 v[136:139], v177, s[0:1] offset:128
	global_load_dwordx4 v[140:143], v177, s[0:1] offset:144
	v_lshl_add_u32 v176, s76, 8, v178
	v_lshlrev_b32_e32 v176, 10, v176
	v_lshl_add_u32 v176, v154, 1, v176
	v_cmp_lt_i32_e32 vcc, v230, v228
	v_pk_mul_f32 v[172:173], v[124:125], v[124:125]
	v_pk_fma_f32 v[172:173], v[126:127], v[126:127], v[172:173]
	v_pk_fma_f32 v[172:173], v[120:121], v[120:121], v[172:173]
	v_pk_fma_f32 v[172:173], v[122:123], v[122:123], v[172:173]
	v_pk_fma_f32 v[172:173], v[92:93], v[92:93], v[172:173]
	v_pk_fma_f32 v[172:173], v[94:95], v[94:95], v[172:173]
	v_pk_fma_f32 v[172:173], v[88:89], v[88:89], v[172:173]
	v_pk_fma_f32 v[172:173], v[90:91], v[90:91], v[172:173]
	v_cndmask_b32_e32 v183, v226, v230, vcc
	v_cmp_lt_i32_e32 vcc, v229, v228
	v_lshlrev_b32_e32 v183, 2, v183
	v_add_f32_e32 v232, v172, v173
	v_pk_mul_f32 v[172:173], v[116:117], v[116:117]
	v_pk_fma_f32 v[172:173], v[118:119], v[118:119], v[172:173]
	v_pk_fma_f32 v[172:173], v[112:113], v[112:113], v[172:173]
	v_pk_fma_f32 v[172:173], v[114:115], v[114:115], v[172:173]
	v_pk_fma_f32 v[172:173], v[84:85], v[84:85], v[172:173]
	v_pk_fma_f32 v[172:173], v[86:87], v[86:87], v[172:173]
	v_pk_fma_f32 v[172:173], v[80:81], v[80:81], v[172:173]
	v_pk_fma_f32 v[172:173], v[82:83], v[82:83], v[172:173]
	v_cndmask_b32_e32 v174, v226, v229, vcc
	v_lshlrev_b32_e32 v174, 2, v174
	v_add_f32_e32 v233, v172, v173
	v_pk_mul_f32 v[172:173], v[108:109], v[108:109]
	v_pk_fma_f32 v[172:173], v[110:111], v[110:111], v[172:173]
	v_pk_fma_f32 v[172:173], v[104:105], v[104:105], v[172:173]
	v_pk_fma_f32 v[172:173], v[106:107], v[106:107], v[172:173]
	v_pk_fma_f32 v[172:173], v[76:77], v[76:77], v[172:173]
	v_pk_fma_f32 v[172:173], v[78:79], v[78:79], v[172:173]
	v_pk_fma_f32 v[172:173], v[72:73], v[72:73], v[172:173]
	v_pk_fma_f32 v[172:173], v[74:75], v[74:75], v[172:173]
	v_add_f32_e32 v234, v172, v173
	v_pk_mul_f32 v[172:173], v[100:101], v[100:101]
	v_pk_fma_f32 v[172:173], v[102:103], v[102:103], v[172:173]
	v_pk_fma_f32 v[172:173], v[96:97], v[96:97], v[172:173]
	v_pk_fma_f32 v[172:173], v[98:99], v[98:99], v[172:173]
	v_pk_fma_f32 v[172:173], v[68:69], v[68:69], v[172:173]
	v_pk_fma_f32 v[172:173], v[70:71], v[70:71], v[172:173]
	v_pk_fma_f32 v[172:173], v[64:65], v[64:65], v[172:173]
	v_pk_fma_f32 v[172:173], v[66:67], v[66:67], v[172:173]
	v_add_f32_e32 v235, v172, v173
	v_pk_mul_f32 v[172:173], v[60:61], v[60:61]
	v_pk_fma_f32 v[172:173], v[62:63], v[62:63], v[172:173]
	v_pk_fma_f32 v[172:173], v[56:57], v[56:57], v[172:173]
	v_pk_fma_f32 v[172:173], v[58:59], v[58:59], v[172:173]
	v_pk_fma_f32 v[172:173], v[28:29], v[28:29], v[172:173]
	v_pk_fma_f32 v[172:173], v[30:31], v[30:31], v[172:173]
	v_pk_fma_f32 v[172:173], v[24:25], v[24:25], v[172:173]
	v_pk_fma_f32 v[172:173], v[26:27], v[26:27], v[172:173]
	v_add_f32_e32 v236, v172, v173
	v_pk_mul_f32 v[172:173], v[52:53], v[52:53]
	v_pk_fma_f32 v[172:173], v[54:55], v[54:55], v[172:173]
	v_pk_fma_f32 v[172:173], v[48:49], v[48:49], v[172:173]
	v_pk_fma_f32 v[172:173], v[50:51], v[50:51], v[172:173]
	v_pk_fma_f32 v[172:173], v[20:21], v[20:21], v[172:173]
	v_pk_fma_f32 v[172:173], v[22:23], v[22:23], v[172:173]
	v_pk_fma_f32 v[172:173], v[16:17], v[16:17], v[172:173]
	v_pk_fma_f32 v[172:173], v[18:19], v[18:19], v[172:173]
	v_add_f32_e32 v237, v172, v173
	v_pk_mul_f32 v[172:173], v[44:45], v[44:45]
	v_pk_fma_f32 v[172:173], v[46:47], v[46:47], v[172:173]
	v_pk_fma_f32 v[172:173], v[40:41], v[40:41], v[172:173]
	v_pk_fma_f32 v[172:173], v[42:43], v[42:43], v[172:173]
	v_pk_fma_f32 v[172:173], v[12:13], v[12:13], v[172:173]
	v_pk_fma_f32 v[172:173], v[14:15], v[14:15], v[172:173]
	v_pk_fma_f32 v[172:173], v[8:9], v[8:9], v[172:173]
	v_pk_fma_f32 v[172:173], v[10:11], v[10:11], v[172:173]
	v_add_f32_e32 v240, v172, v173
	v_pk_mul_f32 v[172:173], v[36:37], v[36:37]
	v_pk_fma_f32 v[172:173], v[38:39], v[38:39], v[172:173]
	v_pk_fma_f32 v[172:173], v[32:33], v[32:33], v[172:173]
	v_pk_fma_f32 v[172:173], v[34:35], v[34:35], v[172:173]
	v_pk_fma_f32 v[172:173], v[4:5], v[4:5], v[172:173]
	v_pk_fma_f32 v[172:173], v[6:7], v[6:7], v[172:173]
	v_pk_fma_f32 v[172:173], v[0:1], v[0:1], v[172:173]
	v_pk_fma_f32 v[172:173], v[2:3], v[2:3], v[172:173]
	v_add_f32_e32 v241, v172, v173
	ds_bpermute_b32 v244, v183, v232
	ds_bpermute_b32 v245, v183, v233
	ds_bpermute_b32 v246, v183, v234
	ds_bpermute_b32 v247, v183, v235
	ds_bpermute_b32 v248, v183, v236
	ds_bpermute_b32 v249, v183, v237
	ds_bpermute_b32 v250, v183, v240
	ds_bpermute_b32 v251, v183, v241
	s_waitcnt lgkmcnt(6)
	v_pk_add_f32 v[232:233], v[232:233], v[244:245]
	s_waitcnt lgkmcnt(4)
	v_pk_add_f32 v[234:235], v[234:235], v[246:247]
	s_waitcnt lgkmcnt(2)
	v_pk_add_f32 v[236:237], v[236:237], v[248:249]
	s_waitcnt lgkmcnt(0)
	v_pk_add_f32 v[240:241], v[240:241], v[250:251]
	ds_bpermute_b32 v244, v174, v232
	ds_bpermute_b32 v245, v174, v233
	ds_bpermute_b32 v246, v174, v234
	ds_bpermute_b32 v247, v174, v235
	ds_bpermute_b32 v248, v174, v236
	ds_bpermute_b32 v249, v174, v237
	ds_bpermute_b32 v250, v174, v240
	ds_bpermute_b32 v251, v174, v241
	s_waitcnt lgkmcnt(6)
	v_pk_add_f32 v[232:233], v[232:233], v[244:245]
	s_waitcnt lgkmcnt(4)
	v_pk_add_f32 v[234:235], v[234:235], v[246:247]
	s_waitcnt lgkmcnt(2)
	v_pk_add_f32 v[236:237], v[236:237], v[248:249]
	s_waitcnt lgkmcnt(0)
	v_pk_add_f32 v[240:241], v[240:241], v[250:251]
	v_mul_f32_e32 v232, 0x3c800000, v232
	v_mul_f32_e32 v233, 0x3c800000, v233
	v_mul_f32_e32 v234, 0x3c800000, v234
	v_mul_f32_e32 v235, 0x3c800000, v235
	v_mul_f32_e32 v236, 0x3c800000, v236
	v_mul_f32_e32 v237, 0x3c800000, v237
	v_mul_f32_e32 v240, 0x3c800000, v240
	v_mul_f32_e32 v241, 0x3c800000, v241
	v_add_f32_e32 v232, 0x358637bd, v232
	v_add_f32_e32 v233, 0x358637bd, v233
	v_add_f32_e32 v234, 0x358637bd, v234
	v_add_f32_e32 v235, 0x358637bd, v235
	v_add_f32_e32 v236, 0x358637bd, v236
	v_add_f32_e32 v237, 0x358637bd, v237
	v_add_f32_e32 v240, 0x358637bd, v240
	v_add_f32_e32 v241, 0x358637bd, v241
	v_rsq_f32_e32 v232, v232
	v_rsq_f32_e32 v233, v233
	v_rsq_f32_e32 v234, v234
	v_rsq_f32_e32 v235, v235
	v_rsq_f32_e32 v236, v236
	v_rsq_f32_e32 v237, v237
	v_rsq_f32_e32 v240, v240
	v_rsq_f32_e32 v241, v241
	v_mul_f32_e32 v232, s9, v232
	v_mul_f32_e32 v233, s9, v233
	v_mul_f32_e32 v234, s9, v234
	v_mul_f32_e32 v235, s9, v235
	v_mul_f32_e32 v236, s9, v236
	v_mul_f32_e32 v237, s9, v237
	v_mul_f32_e32 v240, s9, v240
	v_mul_f32_e32 v241, s9, v241
	s_waitcnt vmcnt(0)
	v_pk_mul_f32 v[244:245], v[128:129], v[232:233] op_sel_hi:[1,0]
	v_pk_mul_f32 v[246:247], v[130:131], v[232:233] op_sel_hi:[1,0]
	v_pk_mul_f32 v[248:249], v[132:133], v[232:233] op_sel_hi:[1,0]
	v_pk_mul_f32 v[250:251], v[134:135], v[232:233] op_sel_hi:[1,0]
	v_pk_mul_f32 v[124:125], v[124:125], v[244:245]
	v_pk_mul_f32 v[126:127], v[126:127], v[246:247]
	v_pk_mul_f32 v[244:245], v[136:137], v[232:233] op_sel_hi:[1,0]
	v_pk_mul_f32 v[246:247], v[138:139], v[232:233] op_sel_hi:[1,0]
	v_pk_mul_f32 v[120:121], v[120:121], v[248:249]
	v_pk_mul_f32 v[122:123], v[122:123], v[250:251]
	v_cvt_pk_bf16_f32 v124, v124, v125
	v_cvt_pk_bf16_f32 v125, v126, v127
	v_pk_mul_f32 v[248:249], v[140:141], v[232:233] op_sel_hi:[1,0]
	v_pk_mul_f32 v[250:251], v[142:143], v[232:233] op_sel_hi:[1,0]
	v_pk_mul_f32 v[92:93], v[92:93], v[244:245]
	v_pk_mul_f32 v[94:95], v[94:95], v[246:247]
	v_cvt_pk_bf16_f32 v126, v120, v121
	v_cvt_pk_bf16_f32 v127, v122, v123
	v_pk_mul_f32 v[244:245], v[128:129], v[232:233] op_sel:[0,1] op_sel_hi:[1,1]
	v_pk_mul_f32 v[246:247], v[130:131], v[232:233] op_sel:[0,1] op_sel_hi:[1,1]
	v_pk_mul_f32 v[88:89], v[88:89], v[248:249]
	v_pk_mul_f32 v[90:91], v[90:91], v[250:251]
	v_cvt_pk_bf16_f32 v92, v92, v93
	v_cvt_pk_bf16_f32 v93, v94, v95
	v_pk_mul_f32 v[248:249], v[132:133], v[232:233] op_sel:[0,1] op_sel_hi:[1,1]
	v_pk_mul_f32 v[250:251], v[134:135], v[232:233] op_sel:[0,1] op_sel_hi:[1,1]
	v_pk_mul_f32 v[116:117], v[116:117], v[244:245]
	v_pk_mul_f32 v[118:119], v[118:119], v[246:247]
	v_cvt_pk_bf16_f32 v94, v88, v89
	v_cvt_pk_bf16_f32 v95, v90, v91
	global_store_dwordx4 v176, v[124:127], s[44:45]
	global_store_dwordx4 v176, v[92:95], s[44:45] offset:64
	s_add_u32 s44, s44, 0x4000
	s_addc_u32 s45, s45, 0
	v_pk_mul_f32 v[244:245], v[136:137], v[232:233] op_sel:[0,1] op_sel_hi:[1,1]
	v_pk_mul_f32 v[246:247], v[138:139], v[232:233] op_sel:[0,1] op_sel_hi:[1,1]
	v_pk_mul_f32 v[112:113], v[112:113], v[248:249]
	v_pk_mul_f32 v[114:115], v[114:115], v[250:251]
	v_cvt_pk_bf16_f32 v116, v116, v117
	v_cvt_pk_bf16_f32 v117, v118, v119
	v_pk_mul_f32 v[248:249], v[140:141], v[232:233] op_sel:[0,1] op_sel_hi:[1,1]
	v_pk_mul_f32 v[250:251], v[142:143], v[232:233] op_sel:[0,1] op_sel_hi:[1,1]
	v_pk_mul_f32 v[84:85], v[84:85], v[244:245]
	v_pk_mul_f32 v[86:87], v[86:87], v[246:247]
	v_cvt_pk_bf16_f32 v118, v112, v113
	v_cvt_pk_bf16_f32 v119, v114, v115
	v_pk_mul_f32 v[244:245], v[128:129], v[234:235] op_sel_hi:[1,0]
	v_pk_mul_f32 v[246:247], v[130:131], v[234:235] op_sel_hi:[1,0]
	v_pk_mul_f32 v[80:81], v[80:81], v[248:249]
	v_pk_mul_f32 v[82:83], v[82:83], v[250:251]
	v_cvt_pk_bf16_f32 v84, v84, v85
	v_cvt_pk_bf16_f32 v85, v86, v87
	v_pk_mul_f32 v[248:249], v[132:133], v[234:235] op_sel_hi:[1,0]
	v_pk_mul_f32 v[250:251], v[134:135], v[234:235] op_sel_hi:[1,0]
	v_pk_mul_f32 v[108:109], v[108:109], v[244:245]
	v_pk_mul_f32 v[110:111], v[110:111], v[246:247]
	v_cvt_pk_bf16_f32 v86, v80, v81
	v_cvt_pk_bf16_f32 v87, v82, v83
	global_store_dwordx4 v176, v[116:119], s[44:45]
	global_store_dwordx4 v176, v[84:87], s[44:45] offset:64
	s_add_u32 s44, s44, 0x4000
	s_addc_u32 s45, s45, 0
	v_pk_mul_f32 v[244:245], v[136:137], v[234:235] op_sel_hi:[1,0]
	v_pk_mul_f32 v[246:247], v[138:139], v[234:235] op_sel_hi:[1,0]
	v_pk_mul_f32 v[104:105], v[104:105], v[248:249]
	v_pk_mul_f32 v[106:107], v[106:107], v[250:251]
	v_cvt_pk_bf16_f32 v108, v108, v109
	v_cvt_pk_bf16_f32 v109, v110, v111
	v_pk_mul_f32 v[248:249], v[140:141], v[234:235] op_sel_hi:[1,0]
	v_pk_mul_f32 v[250:251], v[142:143], v[234:235] op_sel_hi:[1,0]
	v_pk_mul_f32 v[76:77], v[76:77], v[244:245]
	v_pk_mul_f32 v[78:79], v[78:79], v[246:247]
	v_cvt_pk_bf16_f32 v110, v104, v105
	v_cvt_pk_bf16_f32 v111, v106, v107
	v_pk_mul_f32 v[244:245], v[128:129], v[234:235] op_sel:[0,1] op_sel_hi:[1,1]
	v_pk_mul_f32 v[246:247], v[130:131], v[234:235] op_sel:[0,1] op_sel_hi:[1,1]
	v_pk_mul_f32 v[72:73], v[72:73], v[248:249]
	v_pk_mul_f32 v[74:75], v[74:75], v[250:251]
	v_cvt_pk_bf16_f32 v76, v76, v77
	v_cvt_pk_bf16_f32 v77, v78, v79
	v_pk_mul_f32 v[248:249], v[132:133], v[234:235] op_sel:[0,1] op_sel_hi:[1,1]
	v_pk_mul_f32 v[250:251], v[134:135], v[234:235] op_sel:[0,1] op_sel_hi:[1,1]
	v_pk_mul_f32 v[100:101], v[100:101], v[244:245]
	v_pk_mul_f32 v[102:103], v[102:103], v[246:247]
	v_cvt_pk_bf16_f32 v78, v72, v73
	v_cvt_pk_bf16_f32 v79, v74, v75
	global_store_dwordx4 v176, v[108:111], s[44:45]
	global_store_dwordx4 v176, v[76:79], s[44:45] offset:64
	s_add_u32 s44, s44, 0x4000
	s_addc_u32 s45, s45, 0
	v_pk_mul_f32 v[244:245], v[136:137], v[234:235] op_sel:[0,1] op_sel_hi:[1,1]
	v_pk_mul_f32 v[246:247], v[138:139], v[234:235] op_sel:[0,1] op_sel_hi:[1,1]
	v_pk_mul_f32 v[96:97], v[96:97], v[248:249]
	v_pk_mul_f32 v[98:99], v[98:99], v[250:251]
	v_cvt_pk_bf16_f32 v100, v100, v101
	v_cvt_pk_bf16_f32 v101, v102, v103
	v_pk_mul_f32 v[248:249], v[140:141], v[234:235] op_sel:[0,1] op_sel_hi:[1,1]
	v_pk_mul_f32 v[250:251], v[142:143], v[234:235] op_sel:[0,1] op_sel_hi:[1,1]
	v_pk_mul_f32 v[68:69], v[68:69], v[244:245]
	v_pk_mul_f32 v[70:71], v[70:71], v[246:247]
	v_cvt_pk_bf16_f32 v102, v96, v97
	v_cvt_pk_bf16_f32 v103, v98, v99
	v_pk_mul_f32 v[244:245], v[128:129], v[236:237] op_sel_hi:[1,0]
	v_pk_mul_f32 v[246:247], v[130:131], v[236:237] op_sel_hi:[1,0]
	v_pk_mul_f32 v[64:65], v[64:65], v[248:249]
	v_pk_mul_f32 v[66:67], v[66:67], v[250:251]
	v_cvt_pk_bf16_f32 v68, v68, v69
	v_cvt_pk_bf16_f32 v69, v70, v71
	v_pk_mul_f32 v[248:249], v[132:133], v[236:237] op_sel_hi:[1,0]
	v_pk_mul_f32 v[250:251], v[134:135], v[236:237] op_sel_hi:[1,0]
	v_pk_mul_f32 v[60:61], v[60:61], v[244:245]
	v_pk_mul_f32 v[62:63], v[62:63], v[246:247]
	v_cvt_pk_bf16_f32 v70, v64, v65
	v_cvt_pk_bf16_f32 v71, v66, v67
	global_store_dwordx4 v176, v[100:103], s[44:45]
	global_store_dwordx4 v176, v[68:71], s[44:45] offset:64
	s_add_u32 s44, s44, 0x14000
	s_addc_u32 s45, s45, 0
	v_pk_mul_f32 v[244:245], v[136:137], v[236:237] op_sel_hi:[1,0]
	v_pk_mul_f32 v[246:247], v[138:139], v[236:237] op_sel_hi:[1,0]
	v_pk_mul_f32 v[56:57], v[56:57], v[248:249]
	v_pk_mul_f32 v[58:59], v[58:59], v[250:251]
	v_cvt_pk_bf16_f32 v60, v60, v61
	v_cvt_pk_bf16_f32 v61, v62, v63
	v_pk_mul_f32 v[248:249], v[140:141], v[236:237] op_sel_hi:[1,0]
	v_pk_mul_f32 v[250:251], v[142:143], v[236:237] op_sel_hi:[1,0]
	v_pk_mul_f32 v[28:29], v[28:29], v[244:245]
	v_pk_mul_f32 v[30:31], v[30:31], v[246:247]
	v_cvt_pk_bf16_f32 v62, v56, v57
	v_cvt_pk_bf16_f32 v63, v58, v59
	v_pk_mul_f32 v[244:245], v[128:129], v[236:237] op_sel:[0,1] op_sel_hi:[1,1]
	v_pk_mul_f32 v[246:247], v[130:131], v[236:237] op_sel:[0,1] op_sel_hi:[1,1]
	v_pk_mul_f32 v[24:25], v[24:25], v[248:249]
	v_pk_mul_f32 v[26:27], v[26:27], v[250:251]
	v_cvt_pk_bf16_f32 v28, v28, v29
	v_cvt_pk_bf16_f32 v29, v30, v31
	v_pk_mul_f32 v[248:249], v[132:133], v[236:237] op_sel:[0,1] op_sel_hi:[1,1]
	v_pk_mul_f32 v[250:251], v[134:135], v[236:237] op_sel:[0,1] op_sel_hi:[1,1]
	v_pk_mul_f32 v[52:53], v[52:53], v[244:245]
	v_pk_mul_f32 v[54:55], v[54:55], v[246:247]
	v_cvt_pk_bf16_f32 v30, v24, v25
	v_cvt_pk_bf16_f32 v31, v26, v27
	global_store_dwordx4 v176, v[60:63], s[44:45]
	global_store_dwordx4 v176, v[28:31], s[44:45] offset:64
	s_add_u32 s44, s44, 0x4000
	s_addc_u32 s45, s45, 0
	v_pk_mul_f32 v[244:245], v[136:137], v[236:237] op_sel:[0,1] op_sel_hi:[1,1]
	v_pk_mul_f32 v[246:247], v[138:139], v[236:237] op_sel:[0,1] op_sel_hi:[1,1]
	v_pk_mul_f32 v[48:49], v[48:49], v[248:249]
	v_pk_mul_f32 v[50:51], v[50:51], v[250:251]
	v_cvt_pk_bf16_f32 v52, v52, v53
	v_cvt_pk_bf16_f32 v53, v54, v55
	v_pk_mul_f32 v[248:249], v[140:141], v[236:237] op_sel:[0,1] op_sel_hi:[1,1]
	v_pk_mul_f32 v[250:251], v[142:143], v[236:237] op_sel:[0,1] op_sel_hi:[1,1]
	v_pk_mul_f32 v[20:21], v[20:21], v[244:245]
	v_pk_mul_f32 v[22:23], v[22:23], v[246:247]
	v_cvt_pk_bf16_f32 v54, v48, v49
	v_cvt_pk_bf16_f32 v55, v50, v51
	v_pk_mul_f32 v[244:245], v[128:129], v[240:241] op_sel_hi:[1,0]
	v_pk_mul_f32 v[246:247], v[130:131], v[240:241] op_sel_hi:[1,0]
	v_pk_mul_f32 v[16:17], v[16:17], v[248:249]
	v_pk_mul_f32 v[18:19], v[18:19], v[250:251]
	v_cvt_pk_bf16_f32 v20, v20, v21
	v_cvt_pk_bf16_f32 v21, v22, v23
	v_pk_mul_f32 v[248:249], v[132:133], v[240:241] op_sel_hi:[1,0]
	v_pk_mul_f32 v[250:251], v[134:135], v[240:241] op_sel_hi:[1,0]
	v_pk_mul_f32 v[44:45], v[44:45], v[244:245]
	v_pk_mul_f32 v[46:47], v[46:47], v[246:247]
	v_cvt_pk_bf16_f32 v22, v16, v17
	v_cvt_pk_bf16_f32 v23, v18, v19
	global_store_dwordx4 v176, v[52:55], s[44:45]
	global_store_dwordx4 v176, v[20:23], s[44:45] offset:64
	s_add_u32 s44, s44, 0x4000
	s_addc_u32 s45, s45, 0
	v_pk_mul_f32 v[244:245], v[136:137], v[240:241] op_sel_hi:[1,0]
	v_pk_mul_f32 v[246:247], v[138:139], v[240:241] op_sel_hi:[1,0]
	v_pk_mul_f32 v[40:41], v[40:41], v[248:249]
	v_pk_mul_f32 v[42:43], v[42:43], v[250:251]
	v_cvt_pk_bf16_f32 v44, v44, v45
	v_cvt_pk_bf16_f32 v45, v46, v47
	v_pk_mul_f32 v[248:249], v[140:141], v[240:241] op_sel_hi:[1,0]
	v_pk_mul_f32 v[250:251], v[142:143], v[240:241] op_sel_hi:[1,0]
	v_pk_mul_f32 v[12:13], v[12:13], v[244:245]
	v_pk_mul_f32 v[14:15], v[14:15], v[246:247]
	v_cvt_pk_bf16_f32 v46, v40, v41
	v_cvt_pk_bf16_f32 v47, v42, v43
	v_pk_mul_f32 v[244:245], v[128:129], v[240:241] op_sel:[0,1] op_sel_hi:[1,1]
	v_pk_mul_f32 v[246:247], v[130:131], v[240:241] op_sel:[0,1] op_sel_hi:[1,1]
	v_pk_mul_f32 v[8:9], v[8:9], v[248:249]
	v_pk_mul_f32 v[10:11], v[10:11], v[250:251]
	v_cvt_pk_bf16_f32 v12, v12, v13
	v_cvt_pk_bf16_f32 v13, v14, v15
	v_pk_mul_f32 v[248:249], v[132:133], v[240:241] op_sel:[0,1] op_sel_hi:[1,1]
	v_pk_mul_f32 v[250:251], v[134:135], v[240:241] op_sel:[0,1] op_sel_hi:[1,1]
	v_pk_mul_f32 v[36:37], v[36:37], v[244:245]
	v_pk_mul_f32 v[38:39], v[38:39], v[246:247]
	v_cvt_pk_bf16_f32 v14, v8, v9
	v_cvt_pk_bf16_f32 v15, v10, v11
	global_store_dwordx4 v176, v[44:47], s[44:45]
	global_store_dwordx4 v176, v[12:15], s[44:45] offset:64
	s_add_u32 s44, s44, 0x4000
	s_addc_u32 s45, s45, 0
	v_pk_mul_f32 v[244:245], v[136:137], v[240:241] op_sel:[0,1] op_sel_hi:[1,1]
	v_pk_mul_f32 v[246:247], v[138:139], v[240:241] op_sel:[0,1] op_sel_hi:[1,1]
	v_pk_mul_f32 v[32:33], v[32:33], v[248:249]
	v_pk_mul_f32 v[34:35], v[34:35], v[250:251]
	v_cvt_pk_bf16_f32 v36, v36, v37
	v_cvt_pk_bf16_f32 v37, v38, v39
	v_pk_mul_f32 v[248:249], v[140:141], v[240:241] op_sel:[0,1] op_sel_hi:[1,1]
	v_pk_mul_f32 v[250:251], v[142:143], v[240:241] op_sel:[0,1] op_sel_hi:[1,1]
	v_pk_mul_f32 v[4:5], v[4:5], v[244:245]
	v_pk_mul_f32 v[6:7], v[6:7], v[246:247]
	v_cvt_pk_bf16_f32 v38, v32, v33
	v_cvt_pk_bf16_f32 v39, v34, v35
	v_pk_mul_f32 v[0:1], v[0:1], v[248:249]
	v_pk_mul_f32 v[2:3], v[2:3], v[250:251]
	v_cvt_pk_bf16_f32 v4, v4, v5
	v_cvt_pk_bf16_f32 v5, v6, v7
	s_nop 0
	v_cvt_pk_bf16_f32 v6, v0, v1
	v_cvt_pk_bf16_f32 v7, v2, v3
	global_store_dwordx4 v176, v[36:39], s[44:45]
	global_store_dwordx4 v176, v[4:7], s[44:45] offset:64
	s_branch .LBB0_611
